# v067 with the six K-loop heads aligned to 64 bytes
# speedup vs baseline: 1.0031x; 1.0031x over previous
.LBB0_133:
	s_ashr_i32 s19, s18, 31
	s_lshl_b64 s[28:29], s[18:19], 19
	v_cmp_lt_i64_e32 vcc, s[62:63], v[182:183]
	s_add_u32 s62, s27, s28
	s_addc_u32 s63, s37, s29
	s_and_b64 s[28:29], vcc, exec
	s_cselect_b32 s5, s63, s67
	s_cselect_b32 s7, s62, s66
	s_ashr_i32 s17, s16, 31
	s_lshl_b64 s[28:29], s[16:17], 19
	s_add_u32 s64, s46, s28
	s_addc_u32 s65, s47, s29
	s_and_b64 s[28:29], vcc, exec
	s_cselect_b32 s17, s65, s69
	s_cselect_b32 s19, s64, s68
	s_add_u32 s66, s66, 0x40080
	s_addc_u32 s67, s67, 0
	s_add_u32 s85, s68, 0x100
	v_mov_b64_e32 v[0:1], 0
	v_mov_b64_e32 v[2:3], 0
	v_mov_b64_e32 v[4:5], 0
	v_mov_b64_e32 v[6:7], 0
	v_mov_b64_e32 v[8:9], 0
	v_mov_b64_e32 v[10:11], 0
	v_mov_b64_e32 v[12:13], 0
	v_mov_b64_e32 v[14:15], 0
	v_mov_b64_e32 v[16:17], 0
	v_mov_b64_e32 v[18:19], 0
	v_mov_b64_e32 v[20:21], 0
	v_mov_b64_e32 v[22:23], 0
	v_mov_b64_e32 v[24:25], 0
	v_mov_b64_e32 v[26:27], 0
	v_mov_b64_e32 v[28:29], 0
	v_mov_b64_e32 v[30:31], 0
	v_mov_b64_e32 v[32:33], 0
	v_mov_b64_e32 v[34:35], 0
	v_mov_b64_e32 v[36:37], 0
	v_mov_b64_e32 v[38:39], 0
	v_mov_b64_e32 v[40:41], 0
	v_mov_b64_e32 v[42:43], 0
	v_mov_b64_e32 v[44:45], 0
	v_mov_b64_e32 v[46:47], 0
	v_mov_b64_e32 v[48:49], 0
	v_mov_b64_e32 v[50:51], 0
	v_mov_b64_e32 v[52:53], 0
	v_mov_b64_e32 v[54:55], 0
	v_mov_b64_e32 v[56:57], 0
	v_mov_b64_e32 v[58:59], 0
	v_mov_b64_e32 v[60:61], 0
	v_mov_b64_e32 v[62:63], 0
	v_mov_b64_e32 v[64:65], 0
	v_mov_b64_e32 v[66:67], 0
	v_mov_b64_e32 v[68:69], 0
	v_mov_b64_e32 v[70:71], 0
	v_mov_b64_e32 v[72:73], 0
	v_mov_b64_e32 v[74:75], 0
	v_mov_b64_e32 v[76:77], 0
	v_mov_b64_e32 v[78:79], 0
	v_mov_b64_e32 v[80:81], 0
	v_mov_b64_e32 v[82:83], 0
	v_mov_b64_e32 v[84:85], 0
	v_mov_b64_e32 v[86:87], 0
	v_mov_b64_e32 v[88:89], 0
	v_mov_b64_e32 v[90:91], 0
	v_mov_b64_e32 v[92:93], 0
	v_mov_b64_e32 v[94:95], 0
	v_mov_b64_e32 v[96:97], 0
	v_mov_b64_e32 v[98:99], 0
	v_mov_b64_e32 v[100:101], 0
	v_mov_b64_e32 v[102:103], 0
	v_mov_b64_e32 v[104:105], 0
	v_mov_b64_e32 v[106:107], 0
	v_mov_b64_e32 v[108:109], 0
	v_mov_b64_e32 v[110:111], 0
	v_mov_b64_e32 v[112:113], 0
	v_mov_b64_e32 v[114:115], 0
	v_mov_b64_e32 v[116:117], 0
	v_mov_b64_e32 v[118:119], 0
	v_mov_b64_e32 v[120:121], 0
	v_mov_b64_e32 v[122:123], 0
	v_mov_b64_e32 v[124:125], 0
	v_mov_b64_e32 v[126:127], 0
	s_addc_u32 s91, s69, 0
	s_mov_b32 vcc_lo, -2
	s_waitcnt vmcnt(0)
	v_add_u32_e32 v172, 0x10000, v191
	.p2alignl 6, 3212836864

.LBB0_412:
	s_add_i32 s13, s67, -2
	s_add_u32 s85, s62, 0x100
	v_mov_b64_e32 v[0:1], 0
	v_mov_b64_e32 v[2:3], 0
	v_mov_b64_e32 v[4:5], 0
	v_mov_b64_e32 v[6:7], 0
	v_mov_b64_e32 v[8:9], 0
	v_mov_b64_e32 v[10:11], 0
	v_mov_b64_e32 v[12:13], 0
	v_mov_b64_e32 v[14:15], 0
	v_mov_b64_e32 v[16:17], 0
	v_mov_b64_e32 v[18:19], 0
	v_mov_b64_e32 v[20:21], 0
	v_mov_b64_e32 v[22:23], 0
	v_mov_b64_e32 v[24:25], 0
	v_mov_b64_e32 v[26:27], 0
	v_mov_b64_e32 v[28:29], 0
	v_mov_b64_e32 v[30:31], 0
	v_mov_b64_e32 v[32:33], 0
	v_mov_b64_e32 v[34:35], 0
	v_mov_b64_e32 v[36:37], 0
	v_mov_b64_e32 v[38:39], 0
	v_mov_b64_e32 v[40:41], 0
	v_mov_b64_e32 v[42:43], 0
	v_mov_b64_e32 v[44:45], 0
	v_mov_b64_e32 v[46:47], 0
	v_mov_b64_e32 v[48:49], 0
	v_mov_b64_e32 v[50:51], 0
	v_mov_b64_e32 v[52:53], 0
	v_mov_b64_e32 v[54:55], 0
	v_mov_b64_e32 v[56:57], 0
	v_mov_b64_e32 v[58:59], 0
	v_mov_b64_e32 v[60:61], 0
	v_mov_b64_e32 v[62:63], 0
	v_mov_b64_e32 v[64:65], 0
	v_mov_b64_e32 v[66:67], 0
	v_mov_b64_e32 v[68:69], 0
	v_mov_b64_e32 v[70:71], 0
	v_mov_b64_e32 v[72:73], 0
	v_mov_b64_e32 v[74:75], 0
	v_mov_b64_e32 v[76:77], 0
	v_mov_b64_e32 v[78:79], 0
	v_mov_b64_e32 v[80:81], 0
	v_mov_b64_e32 v[82:83], 0
	v_mov_b64_e32 v[84:85], 0
	v_mov_b64_e32 v[86:87], 0
	v_mov_b64_e32 v[88:89], 0
	v_mov_b64_e32 v[90:91], 0
	v_mov_b64_e32 v[92:93], 0
	v_mov_b64_e32 v[94:95], 0
	v_mov_b64_e32 v[96:97], 0
	v_mov_b64_e32 v[98:99], 0
	v_mov_b64_e32 v[100:101], 0
	v_mov_b64_e32 v[102:103], 0
	v_mov_b64_e32 v[104:105], 0
	v_mov_b64_e32 v[106:107], 0
	v_mov_b64_e32 v[108:109], 0
	v_mov_b64_e32 v[110:111], 0
	v_mov_b64_e32 v[112:113], 0
	v_mov_b64_e32 v[114:115], 0
	v_mov_b64_e32 v[116:117], 0
	v_mov_b64_e32 v[118:119], 0
	v_mov_b64_e32 v[120:121], 0
	v_mov_b64_e32 v[122:123], 0
	v_mov_b64_e32 v[124:125], 0
	v_mov_b64_e32 v[126:127], 0
	s_addc_u32 s91, s63, 0
	s_mov_b32 s62, 0
	v_add_u32_e32 v174, 0x10000, v164
	.p2alignl 6, 3212836864

.LBB0_504:
	v_mov_b64_e32 v[0:1], 0x3c6
	s_ashr_i32 s65, s64, 31
	v_cmp_lt_i64_e32 vcc, s[8:9], v[0:1]
	s_lshl_b64 s[8:9], s[64:65], 20
	s_add_u32 s66, s27, s8
	s_addc_u32 s67, s74, s9
	s_and_b64 s[8:9], vcc, exec
	s_cselect_b32 s10, s67, s5
	s_cselect_b32 s11, s66, s4
	s_ashr_i32 s63, s62, 31
	s_lshl_b64 s[8:9], s[62:63], 20
	s_add_u32 s68, s75, s8
	s_addc_u32 s69, s76, s9
	s_and_b64 s[8:9], vcc, exec
	s_cselect_b32 s63, s69, s7
	s_cselect_b32 s65, s68, s6
	s_add_u32 s4, s4, 0x80080
	s_addc_u32 s5, s5, 0
	s_add_u32 s70, s6, 0x100
	v_mov_b64_e32 v[0:1], 0
	v_mov_b64_e32 v[2:3], 0
	v_mov_b64_e32 v[4:5], 0
	v_mov_b64_e32 v[6:7], 0
	v_mov_b64_e32 v[8:9], 0
	v_mov_b64_e32 v[10:11], 0
	v_mov_b64_e32 v[12:13], 0
	v_mov_b64_e32 v[14:15], 0
	v_mov_b64_e32 v[16:17], 0
	v_mov_b64_e32 v[18:19], 0
	v_mov_b64_e32 v[20:21], 0
	v_mov_b64_e32 v[22:23], 0
	v_mov_b64_e32 v[24:25], 0
	v_mov_b64_e32 v[26:27], 0
	v_mov_b64_e32 v[28:29], 0
	v_mov_b64_e32 v[30:31], 0
	v_mov_b64_e32 v[32:33], 0
	v_mov_b64_e32 v[34:35], 0
	v_mov_b64_e32 v[36:37], 0
	v_mov_b64_e32 v[38:39], 0
	v_mov_b64_e32 v[40:41], 0
	v_mov_b64_e32 v[42:43], 0
	v_mov_b64_e32 v[44:45], 0
	v_mov_b64_e32 v[46:47], 0
	v_mov_b64_e32 v[48:49], 0
	v_mov_b64_e32 v[50:51], 0
	v_mov_b64_e32 v[52:53], 0
	v_mov_b64_e32 v[54:55], 0
	v_mov_b64_e32 v[56:57], 0
	v_mov_b64_e32 v[58:59], 0
	v_mov_b64_e32 v[60:61], 0
	v_mov_b64_e32 v[62:63], 0
	v_mov_b64_e32 v[64:65], 0
	v_mov_b64_e32 v[66:67], 0
	v_mov_b64_e32 v[68:69], 0
	v_mov_b64_e32 v[70:71], 0
	v_mov_b64_e32 v[72:73], 0
	v_mov_b64_e32 v[74:75], 0
	v_mov_b64_e32 v[76:77], 0
	v_mov_b64_e32 v[78:79], 0
	v_mov_b64_e32 v[80:81], 0
	v_mov_b64_e32 v[82:83], 0
	v_mov_b64_e32 v[84:85], 0
	v_mov_b64_e32 v[86:87], 0
	v_mov_b64_e32 v[88:89], 0
	v_mov_b64_e32 v[90:91], 0
	v_mov_b64_e32 v[92:93], 0
	v_mov_b64_e32 v[94:95], 0
	v_mov_b64_e32 v[96:97], 0
	v_mov_b64_e32 v[98:99], 0
	v_mov_b64_e32 v[100:101], 0
	v_mov_b64_e32 v[102:103], 0
	v_mov_b64_e32 v[104:105], 0
	v_mov_b64_e32 v[106:107], 0
	v_mov_b64_e32 v[108:109], 0
	v_mov_b64_e32 v[110:111], 0
	v_mov_b64_e32 v[112:113], 0
	v_mov_b64_e32 v[114:115], 0
	v_mov_b64_e32 v[116:117], 0
	v_mov_b64_e32 v[118:119], 0
	v_mov_b64_e32 v[120:121], 0
	v_mov_b64_e32 v[122:123], 0
	v_mov_b64_e32 v[124:125], 0
	v_mov_b64_e32 v[126:127], 0
	s_addc_u32 s71, s7, 0
	s_mov_b32 s72, -2
	v_add_u32_e32 v174, 0x10000, v144
	.p2alignl 6, 3212836864

.LBB0_1113:
	s_add_i32 s85, s76, -2
	s_add_u32 s64, s64, 0x80
	s_addc_u32 s65, s65, 0
	s_add_u32 s91, s66, 0x100
	v_mov_b64_e32 v[0:1], 0
	v_mov_b64_e32 v[2:3], 0
	v_mov_b64_e32 v[4:5], 0
	v_mov_b64_e32 v[6:7], 0
	v_mov_b64_e32 v[8:9], 0
	v_mov_b64_e32 v[10:11], 0
	v_mov_b64_e32 v[12:13], 0
	v_mov_b64_e32 v[14:15], 0
	v_mov_b64_e32 v[16:17], 0
	v_mov_b64_e32 v[18:19], 0
	v_mov_b64_e32 v[20:21], 0
	v_mov_b64_e32 v[22:23], 0
	v_mov_b64_e32 v[24:25], 0
	v_mov_b64_e32 v[26:27], 0
	v_mov_b64_e32 v[28:29], 0
	v_mov_b64_e32 v[30:31], 0
	v_mov_b64_e32 v[32:33], 0
	v_mov_b64_e32 v[34:35], 0
	v_mov_b64_e32 v[36:37], 0
	v_mov_b64_e32 v[38:39], 0
	v_mov_b64_e32 v[40:41], 0
	v_mov_b64_e32 v[42:43], 0
	v_mov_b64_e32 v[44:45], 0
	v_mov_b64_e32 v[46:47], 0
	v_mov_b64_e32 v[48:49], 0
	v_mov_b64_e32 v[50:51], 0
	v_mov_b64_e32 v[52:53], 0
	v_mov_b64_e32 v[54:55], 0
	v_mov_b64_e32 v[56:57], 0
	v_mov_b64_e32 v[58:59], 0
	v_mov_b64_e32 v[60:61], 0
	v_mov_b64_e32 v[62:63], 0
	v_mov_b64_e32 v[64:65], 0
	v_mov_b64_e32 v[66:67], 0
	v_mov_b64_e32 v[68:69], 0
	v_mov_b64_e32 v[70:71], 0
	v_mov_b64_e32 v[72:73], 0
	v_mov_b64_e32 v[74:75], 0
	v_mov_b64_e32 v[76:77], 0
	v_mov_b64_e32 v[78:79], 0
	v_mov_b64_e32 v[80:81], 0
	v_mov_b64_e32 v[82:83], 0
	v_mov_b64_e32 v[84:85], 0
	v_mov_b64_e32 v[86:87], 0
	v_mov_b64_e32 v[88:89], 0
	v_mov_b64_e32 v[90:91], 0
	v_mov_b64_e32 v[92:93], 0
	v_mov_b64_e32 v[94:95], 0
	v_mov_b64_e32 v[96:97], 0
	v_mov_b64_e32 v[98:99], 0
	v_mov_b64_e32 v[100:101], 0
	v_mov_b64_e32 v[102:103], 0
	v_mov_b64_e32 v[104:105], 0
	v_mov_b64_e32 v[106:107], 0
	v_mov_b64_e32 v[108:109], 0
	v_mov_b64_e32 v[110:111], 0
	v_mov_b64_e32 v[112:113], 0
	v_mov_b64_e32 v[114:115], 0
	v_mov_b64_e32 v[116:117], 0
	v_mov_b64_e32 v[118:119], 0
	v_mov_b64_e32 v[120:121], 0
	v_mov_b64_e32 v[122:123], 0
	v_mov_b64_e32 v[124:125], 0
	v_mov_b64_e32 v[126:127], 0
	s_addc_u32 vcc_lo, s67, 0
	s_mov_b32 s66, 0
	v_add_u32_e32 v174, 0x10000, v194
	.p2alignl 6, 3212836864

.LBB0_1281:
	s_add_i32 s5, s79, -2
	s_add_u32 s58, s58, 0x80
	s_addc_u32 s59, s59, 0
	s_add_u32 s21, s60, 0x100
	v_mov_b64_e32 v[0:1], 0
	v_mov_b64_e32 v[2:3], 0
	v_mov_b64_e32 v[4:5], 0
	v_mov_b64_e32 v[6:7], 0
	v_mov_b64_e32 v[8:9], 0
	v_mov_b64_e32 v[10:11], 0
	v_mov_b64_e32 v[12:13], 0
	v_mov_b64_e32 v[14:15], 0
	v_mov_b64_e32 v[16:17], 0
	v_mov_b64_e32 v[18:19], 0
	v_mov_b64_e32 v[20:21], 0
	v_mov_b64_e32 v[22:23], 0
	v_mov_b64_e32 v[24:25], 0
	v_mov_b64_e32 v[26:27], 0
	v_mov_b64_e32 v[28:29], 0
	v_mov_b64_e32 v[30:31], 0
	v_mov_b64_e32 v[32:33], 0
	v_mov_b64_e32 v[34:35], 0
	v_mov_b64_e32 v[36:37], 0
	v_mov_b64_e32 v[38:39], 0
	v_mov_b64_e32 v[40:41], 0
	v_mov_b64_e32 v[42:43], 0
	v_mov_b64_e32 v[44:45], 0
	v_mov_b64_e32 v[46:47], 0
	v_mov_b64_e32 v[48:49], 0
	v_mov_b64_e32 v[50:51], 0
	v_mov_b64_e32 v[52:53], 0
	v_mov_b64_e32 v[54:55], 0
	v_mov_b64_e32 v[56:57], 0
	v_mov_b64_e32 v[58:59], 0
	v_mov_b64_e32 v[60:61], 0
	v_mov_b64_e32 v[62:63], 0
	v_mov_b64_e32 v[64:65], 0
	v_mov_b64_e32 v[66:67], 0
	v_mov_b64_e32 v[68:69], 0
	v_mov_b64_e32 v[70:71], 0
	v_mov_b64_e32 v[72:73], 0
	v_mov_b64_e32 v[74:75], 0
	v_mov_b64_e32 v[76:77], 0
	v_mov_b64_e32 v[78:79], 0
	v_mov_b64_e32 v[80:81], 0
	v_mov_b64_e32 v[82:83], 0
	v_mov_b64_e32 v[84:85], 0
	v_mov_b64_e32 v[86:87], 0
	v_mov_b64_e32 v[88:89], 0
	v_mov_b64_e32 v[90:91], 0
	v_mov_b64_e32 v[92:93], 0
	v_mov_b64_e32 v[94:95], 0
	v_mov_b64_e32 v[96:97], 0
	v_mov_b64_e32 v[98:99], 0
	v_mov_b64_e32 v[100:101], 0
	v_mov_b64_e32 v[102:103], 0
	v_mov_b64_e32 v[104:105], 0
	v_mov_b64_e32 v[106:107], 0
	v_mov_b64_e32 v[108:109], 0
	v_mov_b64_e32 v[110:111], 0
	v_mov_b64_e32 v[112:113], 0
	v_mov_b64_e32 v[114:115], 0
	v_mov_b64_e32 v[116:117], 0
	v_mov_b64_e32 v[118:119], 0
	v_mov_b64_e32 v[120:121], 0
	v_mov_b64_e32 v[122:123], 0
	v_mov_b64_e32 v[124:125], 0
	v_mov_b64_e32 v[126:127], 0
	s_addc_u32 s80, s61, 0
	s_mov_b32 s60, 0
	s_waitcnt lgkmcnt(0)
	v_add_u32_e32 v174, 0x10000, v195
	.p2alignl 6, 3212836864

.LBB0_1435:
	s_ashr_i32 s17, s16, 31
	v_cmp_lt_i64_e32 vcc, s[18:19], v[186:187]
	s_lshl_b64 s[18:19], s[16:17], 19
	s_add_u32 s18, s47, s18
	s_addc_u32 s19, s54, s19
	s_and_b64 s[20:21], vcc, exec
	s_cselect_b32 s17, s19, s7
	s_cselect_b32 s66, s18, s6
	s_ashr_i32 s13, s12, 31
	s_lshl_b64 s[20:21], s[12:13], 19
	s_add_u32 s20, s37, s20
	s_addc_u32 s21, s46, s21
	s_and_b64 s[52:53], vcc, exec
	s_cselect_b32 s13, s21, s51
	s_cselect_b32 s67, s20, s50
	s_add_u32 s6, s6, 0x40080
	s_addc_u32 s7, s7, 0
	s_add_u32 s68, s50, 0x100
	v_mov_b64_e32 v[0:1], 0
	v_mov_b64_e32 v[2:3], 0
	v_mov_b64_e32 v[4:5], 0
	v_mov_b64_e32 v[6:7], 0
	v_mov_b64_e32 v[8:9], 0
	v_mov_b64_e32 v[10:11], 0
	v_mov_b64_e32 v[12:13], 0
	v_mov_b64_e32 v[14:15], 0
	v_mov_b64_e32 v[16:17], 0
	v_mov_b64_e32 v[18:19], 0
	v_mov_b64_e32 v[20:21], 0
	v_mov_b64_e32 v[22:23], 0
	v_mov_b64_e32 v[24:25], 0
	v_mov_b64_e32 v[26:27], 0
	v_mov_b64_e32 v[28:29], 0
	v_mov_b64_e32 v[30:31], 0
	v_mov_b64_e32 v[32:33], 0
	v_mov_b64_e32 v[34:35], 0
	v_mov_b64_e32 v[36:37], 0
	v_mov_b64_e32 v[38:39], 0
	v_mov_b64_e32 v[40:41], 0
	v_mov_b64_e32 v[42:43], 0
	v_mov_b64_e32 v[44:45], 0
	v_mov_b64_e32 v[46:47], 0
	v_mov_b64_e32 v[48:49], 0
	v_mov_b64_e32 v[50:51], 0
	v_mov_b64_e32 v[52:53], 0
	v_mov_b64_e32 v[54:55], 0
	v_mov_b64_e32 v[56:57], 0
	v_mov_b64_e32 v[58:59], 0
	v_mov_b64_e32 v[60:61], 0
	v_mov_b64_e32 v[62:63], 0
	v_mov_b64_e32 v[64:65], 0
	v_mov_b64_e32 v[66:67], 0
	v_mov_b64_e32 v[68:69], 0
	v_mov_b64_e32 v[70:71], 0
	v_mov_b64_e32 v[72:73], 0
	v_mov_b64_e32 v[74:75], 0
	v_mov_b64_e32 v[76:77], 0
	v_mov_b64_e32 v[78:79], 0
	v_mov_b64_e32 v[80:81], 0
	v_mov_b64_e32 v[82:83], 0
	v_mov_b64_e32 v[84:85], 0
	v_mov_b64_e32 v[86:87], 0
	v_mov_b64_e32 v[88:89], 0
	v_mov_b64_e32 v[90:91], 0
	v_mov_b64_e32 v[92:93], 0
	v_mov_b64_e32 v[94:95], 0
	v_mov_b64_e32 v[96:97], 0
	v_mov_b64_e32 v[98:99], 0
	v_mov_b64_e32 v[100:101], 0
	v_mov_b64_e32 v[102:103], 0
	v_mov_b64_e32 v[104:105], 0
	v_mov_b64_e32 v[106:107], 0
	v_mov_b64_e32 v[108:109], 0
	v_mov_b64_e32 v[110:111], 0
	v_mov_b64_e32 v[112:113], 0
	v_mov_b64_e32 v[114:115], 0
	v_mov_b64_e32 v[116:117], 0
	v_mov_b64_e32 v[118:119], 0
	v_mov_b64_e32 v[120:121], 0
	v_mov_b64_e32 v[122:123], 0
	v_mov_b64_e32 v[124:125], 0
	v_mov_b64_e32 v[126:127], 0
	s_addc_u32 s69, s51, 0
	s_mov_b32 s70, -2
	v_add_u32_e32 v174, 0x10000, v200
	.p2alignl 6, 3212836864
